# v30 + GLA prep gate dots: compiler's pk_mul + two adds for terms 8..15 replaced by fma/fmac (single rounding per term, like terms 0..7)
# speedup vs baseline: 1.0062x; 1.0062x over previous
; LPHASE void phase_gla_prep(char* ws_, const float* x_, float* out_, const float* meta_, int nseq_, char* lds) {
;     ...
;       for (int ii = 0; ii < 16; ++ii) { const int i = ig * 16 + ii; float sf = bfv, sb = bbv; const float* a = af + i * 32;
; #pragma unroll
;         for (int k = 0; k < 16; ++k) { sf += a[k] * wf[k]; sb += a[16 + k] * wb[k]; }
;         float lf = (fminf(sf, 0.f) - __logf(1.f + __expf(-fabsf(sf)))) * (1.f / 16.f), lb = (fminf(sb, 0.f) - __logf(1.f + __expf(-fabsf(sb)))) * (1.f / 16.f);
;         if (ismeta && i >= 16) { lf = 0.f; lb = 0.f; }
;         lgF[i * LGP + d] = lf; lgB[i * LGP + d] = lb; tfl += lf; tbl += lb; }
.LBB0_506:
	v_add_u32_e32 v85, s12, v80
	v_add_u32_e32 v96, 0x10200, v85
	ds_read_b128 v[100:103], v96
	ds_read_b128 v[104:107], v96 offset:64
	ds_read_b128 v[108:111], v96 offset:16
	ds_read_b128 v[112:115], v96 offset:80
	ds_read_b128 v[116:119], v96 offset:32
	ds_read_b128 v[120:123], v96 offset:96
	ds_read_b128 v[124:127], v96 offset:48
	ds_read_b128 v[128:131], v96 offset:112
	ds_read_b128 v[136:139], v96 offset:128
	ds_read_b128 v[140:143], v96 offset:192
	ds_read_b128 v[144:147], v96 offset:144
	ds_read_b128 v[148:151], v96 offset:208
	ds_read_b128 v[152:155], v96 offset:160
	ds_read_b128 v[156:159], v96 offset:224
	ds_read_b128 v[160:163], v96 offset:176
	ds_read_b128 v[164:167], v96 offset:240
	s_waitcnt vmcnt(0) lgkmcnt(0)
	s_addk_i32 s12, 0x100
	v_fma_f32 v94, v74, v100, v78
	v_fmac_f32_e32 v94, v77, v101
	v_fmac_f32_e32 v94, v62, v102
	v_fmac_f32_e32 v94, v70, v103
	v_fma_f32 v95, v75, v104, v79
	v_fmac_f32_e32 v95, v76, v105
	v_fmac_f32_e32 v95, v63, v106
	v_fmac_f32_e32 v95, v71, v107
	v_fmac_f32_e32 v94, v64, v108
	v_fmac_f32_e32 v94, v68, v109
	v_fmac_f32_e32 v94, v67, v110
	v_fmac_f32_e32 v94, v72, v111
	v_fmac_f32_e32 v95, v65, v112
	v_fmac_f32_e32 v95, v66, v113
	v_fmac_f32_e32 v95, v69, v114
	v_fmac_f32_e32 v95, v73, v115
	v_fma_f32 v94, v4, v116, v94
	v_fmac_f32_e32 v94, v5, v117
	v_fma_f32 v90, v6, v120, v95
	v_fmac_f32_e32 v90, v7, v121
	v_fma_f32 v91, v8, v118, v94
	v_fmac_f32_e32 v91, v9, v119
	v_fma_f32 v94, v10, v122, v90
	v_fmac_f32_e32 v94, v11, v123
	v_fma_f32 v95, v12, v124, v91
	v_fmac_f32_e32 v95, v13, v125
	v_fma_f32 v90, v14, v128, v94
	v_fmac_f32_e32 v90, v15, v129
	v_fma_f32 v88, v22, v126, v95
	v_fmac_f32_e32 v88, v23, v127
	v_fma_f32 v86, v24, v130, v90
	v_fmac_f32_e32 v86, v25, v131
	v_min_f32_e32 v87, 0, v88
	v_mul_f32_e64 v88, |v88|, s6
	v_exp_f32_e32 v88, v88
	s_nop 0
	v_add_f32_e32 v88, 1.0, v88
	v_log_f32_e32 v88, v88
	s_nop 0
	v_mul_f32_e32 v89, 0x3f317217, v88
	v_fma_f32 v89, v88, s13, -v89
	v_fmac_f32_e32 v89, 0x3377d1cf, v88
	v_fmac_f32_e32 v89, 0x3f317217, v88
	v_mov_b32_e32 v88, v89
	v_sub_f32_e32 v87, v87, v88
	v_min_f32_e32 v88, 0, v86
	v_mul_f32_e64 v86, |v86|, s6
	v_exp_f32_e32 v86, v86
	v_mul_f32_e32 v87, 0x3d800000, v87
	v_add_f32_e32 v86, 1.0, v86
	v_log_f32_e32 v86, v86
	s_nop 0
	v_mul_f32_e32 v89, 0x3f317217, v86
	v_fma_f32 v89, v86, s13, -v89
	v_fmac_f32_e32 v89, 0x3377d1cf, v86
	v_fmac_f32_e32 v89, 0x3f317217, v86
	v_mov_b32_e32 v86, v89
	v_sub_f32_e32 v86, v88, v86
	v_cmp_lt_i32_e32 vcc, 15, v82
	v_mul_f32_e32 v86, 0x3d800000, v86
	s_and_b64 s[0:1], s[26:27], vcc
	v_cndmask_b32_e64 v86, v86, 0, s[0:1]
	v_cndmask_b32_e64 v87, v87, 0, s[0:1]
	ds_write_b32 v81, v87
	ds_write_b32 v81, v86 offset:33024
	v_add_f32_e32 v84, v84, v86
	v_add_f32_e32 v83, v83, v87
	v_fma_f32 v94, v74, v136, v78
	v_fmac_f32_e32 v94, v77, v137
	v_fmac_f32_e32 v94, v62, v138
	v_fmac_f32_e32 v94, v70, v139
	v_fma_f32 v95, v75, v140, v79
	v_fmac_f32_e32 v95, v76, v141
	v_fmac_f32_e32 v95, v63, v142
	v_fmac_f32_e32 v95, v71, v143
	v_fmac_f32_e32 v94, v64, v144
	v_fmac_f32_e32 v94, v68, v145
	v_fmac_f32_e32 v94, v67, v146
	v_fmac_f32_e32 v94, v72, v147
	v_fmac_f32_e32 v95, v65, v148
	v_fmac_f32_e32 v95, v66, v149
	v_fmac_f32_e32 v95, v69, v150
	v_fmac_f32_e32 v95, v73, v151
	v_fma_f32 v94, v4, v152, v94
	v_fmac_f32_e32 v94, v5, v153
	v_fma_f32 v90, v6, v156, v95
	v_fmac_f32_e32 v90, v7, v157
	v_fma_f32 v91, v8, v154, v94
	v_fmac_f32_e32 v91, v9, v155
	v_fma_f32 v94, v10, v158, v90
	v_fmac_f32_e32 v94, v11, v159
	v_fma_f32 v95, v12, v160, v91
	v_fmac_f32_e32 v95, v13, v161
	v_fma_f32 v85, v14, v164, v94
	v_fmac_f32_e32 v85, v15, v165
	v_fma_f32 v88, v22, v162, v95
	v_fmac_f32_e32 v88, v23, v163
	v_fma_f32 v85, v24, v166, v85
	v_fmac_f32_e32 v85, v25, v167
	v_mul_f32_e64 v87, |v88|, s6
	v_exp_f32_e32 v87, v87
	v_min_f32_e32 v86, 0, v88
	v_add_f32_e32 v87, 1.0, v87
	v_log_f32_e32 v87, v87
	s_nop 0
	v_mul_f32_e32 v88, 0x3f317217, v87
	v_fma_f32 v88, v87, s13, -v88
	v_fmac_f32_e32 v88, 0x3377d1cf, v87
	v_fmac_f32_e32 v88, 0x3f317217, v87
	v_mov_b32_e32 v87, v88
	v_sub_f32_e32 v86, v86, v87
	v_min_f32_e32 v87, 0, v85
	v_mul_f32_e64 v85, |v85|, s6
	v_exp_f32_e32 v85, v85
	v_mul_f32_e32 v86, 0x3d800000, v86
	v_add_f32_e32 v85, 1.0, v85
	v_log_f32_e32 v85, v85
	s_nop 0
	v_mul_f32_e32 v88, 0x3f317217, v85
	v_fma_f32 v88, v85, s13, -v88
	v_fmac_f32_e32 v88, 0x3377d1cf, v85
	v_fmac_f32_e32 v88, 0x3f317217, v85
	v_mov_b32_e32 v85, v88
	v_sub_f32_e32 v85, v87, v85
	v_cmp_lt_i32_e32 vcc, 14, v82
	v_mul_f32_e32 v85, 0x3d800000, v85
	s_and_b64 s[0:1], s[26:27], vcc
	v_cndmask_b32_e64 v85, v85, 0, s[0:1]
	v_cndmask_b32_e64 v86, v86, 0, s[0:1]
	ds_write_b32 v81, v86 offset:516
	ds_write_b32 v81, v85 offset:33540
	v_add_f32_e32 v83, v83, v86
	v_add_f32_e32 v84, v84, v85
	v_add_u32_e32 v82, 2, v82
	v_add_u32_e32 v81, 0x408, v81
	s_cmpk_eq_i32 s12, 0x800
	s_cbranch_scc0 .LBB0_506
	v_and_b32_e32 v4, 0x3fffff80, v16
	v_lshl_add_u32 v6, v2, 2, s85
	v_lshl_add_u32 v5, v16, 2, s85
	v_lshl_add_u32 v4, v4, 2, v6
	ds_write_b32 v5, v83
	ds_write_b32 v4, v84 offset:2048
	s_waitcnt lgkmcnt(0)
	s_barrier
	ds_read2st64_b32 v[10:11], v6 offset1:2
	ds_read2st64_b32 v[8:9], v6 offset0:4 offset1:6
	ds_read2st64_b32 v[4:5], v6 offset0:8 offset1:10
	ds_read2st64_b32 v[6:7], v6 offset0:12 offset1:14
	s_movk_i32 s0, 0x80
	v_cmp_gt_u32_e32 vcc, s0, v16
	s_movk_i32 s0, 0x7f
	s_waitcnt lgkmcnt(3)
	v_add_f32_e32 v11, v10, v11
	v_cmp_lt_u32_e64 s[0:1], s0, v16
	v_mov_b32_e32 v13, 0
	s_and_saveexec_b64 s[26:27], s[0:1]
	s_cbranch_execz .LBB0_513
	v_cmp_lt_i32_e64 s[0:1], 1, v49
	s_mov_b64 s[28:29], 0
	s_and_saveexec_b64 s[30:31], s[0:1]
	s_xor_b64 s[42:43], exec, s[30:31]
	s_cbranch_execnz .LBB0_527
	s_or_saveexec_b64 s[42:43], s[42:43]
	v_mov_b32_e32 v13, v11
	s_xor_b64 exec, exec, s[42:43]
	s_cbranch_execnz .LBB0_530
